# g3 + SwiGLU epilogue: -log2e folded into W1 gate rows (inverse into up rows) at the bf16 weight conversion, one multiply per hidden unit removed
# baseline (speedup 1.0000x reference)
; DI unsigned pk2(float lo, float hi) { f32x2 v = {lo, hi}; bf16x2v b = __builtin_convertvector(v, bf16x2v); return __builtin_bit_cast(unsigned, b); }
; DI int tid_l() { int t = threadIdx.x; asm volatile("" : "+v"(t)); return t; }
; DI int perm32(int rho) { return (((rho >> 2) & 1) << 4) + (rho & 3) + ((rho >> 3) << 2); }
; DI void convert_w(const float* __restrict__ w, bf16_t* __restrict__ wt, int K, int N, int Npad, int mode, float* tl) {
;   const int tid = tid_l();
;   const int nkt = K >> 6, nnt = Npad >> 6;
;   for (int tile = blockIdx.x; tile < nkt * nnt; tile += gridDim.x) {
;     const int k0 = (tile / nnt) << 6, n0 = (tile % nnt) << 6;
; #pragma unroll
;     for (int i = 0; i < 2; ++i) {
;       const int kk = (tid >> 4) + 32 * i, n4 = (tid & 15) << 2;
;       const int np = n0 + n4;
;       int src = np;
;       if (mode == 1) { const int grp = np >> 6, j = np & 63; src = (j < 32) ? grp * 32 + perm32(j) : DFF + grp * 32 + perm32(j - 32); }
;       else if (mode == 2) src = (np & ~31) + perm32(np & 31);
;       f32x4 v = {0.f, 0.f, 0.f, 0.f};
;       if (src < N) v = *(const f32x4*)(w + (size_t)(k0 + kk) * N + src);
;       tl[kk * 65 + n4 + 0] = v[0]; tl[kk * 65 + n4 + 1] = v[1]; tl[kk * 65 + n4 + 2] = v[2]; tl[kk * 65 + n4 + 3] = v[3];
;     }
;     __syncthreads();
;     {
;       const int n = tid >> 3, kc = (tid & 7) << 3;
;       float f[8];
; #pragma unroll
;       for (int j = 0; j < 8; ++j) f[j] = tl[(kc + j) * 65 + n];
;       u32x4 o = {pk2(f[0], f[1]), pk2(f[2], f[3]), pk2(f[4], f[5]), pk2(f[6], f[7])};
;       *(u32x4*)(wt + (size_t)(n0 + n) * K + k0 + kc) = o;
;     }
;     __syncthreads();
.LBB0_27:
	s_mul_hi_u32 s50, s45, 0xb00000
	s_mul_i32 s51, s45, 0xb00000
	v_mov_b32_e32 v2, v192
	s_and_b64 vcc, exec, s[4:5]
	s_cbranch_vccnz .LBB0_32
	s_mul_i32 s9, s45, 0x1600000
	s_mul_hi_u32 s8, s45, 0x1600000
	s_add_u32 s14, s40, s9
	s_addc_u32 s15, s41, s8
	s_load_dword s28, s[80:81], 0x0
	s_load_dword s8, s[80:81], 0x10
	v_lshlrev_b32_e32 v3, 2, v2
	s_add_u32 s16, s3, s51
	v_and_b32_e32 v3, 60, v3
	s_addc_u32 s17, s33, s50
	v_lshlrev_b32_e32 v4, 2, v3
	s_waitcnt lgkmcnt(0)
	s_lshr_b32 s8, s8, 16
	v_ashrrev_i32_e32 v1, 4, v2
	v_add_u32_e32 v5, 0, v4
	v_lshlrev_b32_e32 v6, 1, v2
	v_cmp_gt_u32_e32 vcc, 32, v3
	v_and_b32_e32 v3, 16, v4
	v_ashrrev_i32_e32 v4, 3, v2
	v_lshlrev_b32_e32 v2, 3, v2
	s_cmp_lg_u32 s8, 0
	v_and_b32_e32 v2, 56, v2
	s_cselect_b64 s[8:9], -1, 0
	v_lshl_add_u32 v7, v4, 2, 0
	s_cmp_lg_u64 s[8:9], 0
	v_mul_u32_u24_e32 v8, 0x104, v2
	v_mul_lo_u32 v9, v1, s46
	v_and_b32_e32 v6, 12, v6
	s_addc_u32 s52, s28, 0
	v_add_u32_e32 v16, v5, v9
	v_add_u32_e32 v19, v7, v8
	v_add3_u32 v14, s44, v3, v6
	s_lshl_b32 s53, s52, 5
	v_add_u32_e32 v15, s76, v4
	s_lshl_b32 s54, s52, 6
	v_add_u32_e32 v17, 0x2080, v16
	v_add_u32_e32 v18, 0x2088, v16
	v_lshlrev_b32_e32 v10, 1, v2
	v_add_u32_e32 v20, 0x400, v19
	s_mov_b32 s55, s2
	v_lshrrev_b32_e32 v58, 8, v192
	v_mov_b32_e32 v59, 0xbf317218
	v_mov_b32_e32 v60, 0xbfb8aa3b
	v_cmp_eq_u32_e64 s[98:99], 0, v58
	s_nop 1
	v_cndmask_b32_e64 v58, v59, v60, s[98:99]
	s_branch .LBB0_30
.LBB0_29:
	s_or_b64 exec, exec, s[30:31]
	s_waitcnt vmcnt(1)
	ds_write2_b32 v16, v6, v7 offset1:1
	ds_write2_b32 v16, v8, v9 offset0:2 offset1:3
	s_waitcnt vmcnt(0)
	ds_write2_b32 v17, v2, v3 offset1:1
	ds_write2_b32 v18, v4, v5 offset1:1
	s_waitcnt lgkmcnt(0)
	s_barrier
	ds_read2_b32 v[2:3], v19 offset1:65
	ds_read2_b32 v[4:5], v19 offset0:130 offset1:195
	ds_read2_b32 v[6:7], v20 offset0:4 offset1:69
	ds_read2_b32 v[8:9], v20 offset0:134 offset1:199
	s_mulk_i32 s29, 0xea00
	s_waitcnt lgkmcnt(3)
	v_mul_f32_e32 v2, v58, v2
	v_mul_f32_e32 v3, v58, v3
	v_cvt_pk_bf16_f32 v2, v2, v3
	s_waitcnt lgkmcnt(2)
	v_mul_f32_e32 v4, v58, v4
	v_mul_f32_e32 v5, v58, v5
	v_cvt_pk_bf16_f32 v3, v4, v5
	s_waitcnt lgkmcnt(1)
	v_mul_f32_e32 v6, v58, v6
	v_mul_f32_e32 v7, v58, v7
	v_cvt_pk_bf16_f32 v4, v6, v7
	v_add_u32_e32 v6, s29, v15
	v_ashrrev_i32_e32 v7, 31, v6
	v_lshlrev_b64 v[6:7], 11, v[6:7]
	v_lshl_add_u64 v[6:7], s[16:17], 0, v[6:7]
	s_ashr_i32 s29, s28, 31
	v_lshl_add_u64 v[6:7], s[28:29], 1, v[6:7]
	s_add_i32 s55, s55, s52
	s_waitcnt lgkmcnt(0)
	v_mul_f32_e32 v8, v58, v8
	v_mul_f32_e32 v9, v58, v9
	v_cvt_pk_bf16_f32 v5, v8, v9
	v_lshl_add_u64 v[6:7], v[6:7], 0, v[10:11]
	v_add_u32_e32 v14, s53, v14
	s_cmpk_lt_i32 s55, 0x580
	v_add_u32_e32 v15, s54, v15
	global_store_dwordx4 v[6:7], v[2:5], off
	s_barrier
	s_cbranch_scc0 .LBB0_32

; DI unsigned pk2(float lo, float hi) { f32x2 v = {lo, hi}; bf16x2v b = __builtin_convertvector(v, bf16x2v); return __builtin_bit_cast(unsigned, b); }
; DI float siluf_(float x) { return x * __builtin_amdgcn_rcpf(1.f + __builtin_amdgcn_exp2f(-LOG2E * x)); }
;   DI void operator()(int tok0, int feat0, f32x16 (&acc)[2][2], int r, int hh) const {
;     const int u0 = (feat0 >> 6) * 32;
; #pragma unroll
;     for (int mt = 0; mt < 2; ++mt) {
;       bf16_t* dst = act + (size_t)(tok0 + mt * 32 + r) * DFF + u0 + 16 * hh;
; #pragma unroll
;       for (int gp = 0; gp < 2; ++gp) {
;         u32x4 o;
; #pragma unroll
;         for (int q = 0; q < 4; ++q) { const int i = 8 * gp + 2 * q; o[q] = pk2(siluf_(acc[0][mt][i]) * acc[1][mt][i], siluf_(acc[0][mt][i + 1]) * acc[1][mt][i + 1]); }
;         *(u32x4*)(dst + 8 * gp) = o;
;       }
;     }
;   }
.Lkexit_4:
	v_mov_b32_e32 v0, v192
	v_mov_b64_e32 v[166:167], s[6:7]
	v_ashrrev_i32_e32 v164, 1, v0
	v_and_b32_e32 v164, 0xffffff80, v164
	v_add_u32_e32 v164, s3, v164
	v_ashrrev_i32_e32 v164, 1, v164
	v_and_b32_e32 v165, 0xdf, v0
	v_or_b32_e32 v187, s8, v165
	v_ashrrev_i32_e32 v165, 31, v164
	v_mad_i64_i32 v[188:189], s[12:13], v187, s69, v[166:167]
	v_lshlrev_b64 v[168:169], 1, v[164:165]
	v_lshl_add_u64 v[164:165], v[188:189], 0, v[168:169]
	v_exp_f32_e32 v188, v114
	v_exp_f32_e32 v189, v115
	v_and_b32_e32 v0, 32, v0
	v_lshl_add_u64 v[164:165], v[164:165], 0, v[0:1]
	v_add_f32_e32 v188, 1.0, v188
	v_add_f32_e32 v189, 1.0, v189
	v_rcp_f32_e32 v188, v188
	v_rcp_f32_e32 v189, v189
	s_nop 0
	v_pk_mul_f32 v[114:115], v[114:115], v[188:189]
	s_nop 0
	v_pk_mul_f32 v[98:99], v[98:99], v[114:115]
	s_nop 0
	v_cvt_pk_bf16_f32 v98, v98, v99
	v_exp_f32_e32 v99, v116
	s_nop 0
	v_add_f32_e32 v99, 1.0, v99
	v_rcp_f32_e32 v114, v99
	v_exp_f32_e32 v99, v117
	s_nop 0
	v_add_f32_e32 v99, 1.0, v99
	v_rcp_f32_e32 v115, v99
	s_nop 0
	v_pk_mul_f32 v[114:115], v[116:117], v[114:115]
	s_nop 0
	v_pk_mul_f32 v[100:101], v[100:101], v[114:115]
	s_nop 0
	v_cvt_pk_bf16_f32 v99, v100, v101
	v_exp_f32_e32 v100, v118
	v_exp_f32_e32 v101, v119
	v_add_f32_e32 v100, 1.0, v100
	v_add_f32_e32 v101, 1.0, v101
	v_rcp_f32_e32 v100, v100
	v_rcp_f32_e32 v101, v101
	s_nop 0
	v_pk_mul_f32 v[100:101], v[118:119], v[100:101]
	s_nop 0
	v_pk_mul_f32 v[100:101], v[102:103], v[100:101]
	s_nop 0
	v_cvt_pk_bf16_f32 v100, v100, v101
	v_exp_f32_e32 v101, v120
	s_nop 0
	v_add_f32_e32 v101, 1.0, v101
	v_rcp_f32_e32 v102, v101
	v_exp_f32_e32 v101, v121
	s_nop 0
	v_add_f32_e32 v101, 1.0, v101
	v_rcp_f32_e32 v103, v101
	s_nop 0
	v_pk_mul_f32 v[102:103], v[120:121], v[102:103]
	s_nop 0
	v_pk_mul_f32 v[102:103], v[104:105], v[102:103]
	s_nop 0
	v_cvt_pk_bf16_f32 v101, v102, v103
	global_store_dwordx4 v[164:165], v[98:101], off
	s_nop 1
	v_exp_f32_e32 v98, v122
	v_exp_f32_e32 v99, v123
	v_add_f32_e32 v98, 1.0, v98
	v_add_f32_e32 v99, 1.0, v99
	v_rcp_f32_e32 v98, v98
	v_rcp_f32_e32 v99, v99
	s_nop 0
	v_pk_mul_f32 v[98:99], v[122:123], v[98:99]
	s_nop 0
	v_pk_mul_f32 v[98:99], v[106:107], v[98:99]
	s_nop 0
	v_cvt_pk_bf16_f32 v98, v98, v99
	v_exp_f32_e32 v99, v124
	s_nop 0
	v_add_f32_e32 v99, 1.0, v99
	v_rcp_f32_e32 v100, v99
	v_exp_f32_e32 v99, v125
	s_nop 0
	v_add_f32_e32 v99, 1.0, v99
	v_rcp_f32_e32 v101, v99
	s_nop 0
	v_pk_mul_f32 v[100:101], v[124:125], v[100:101]
	s_nop 0
	v_pk_mul_f32 v[100:101], v[108:109], v[100:101]
	s_nop 0
	v_cvt_pk_bf16_f32 v99, v100, v101
	v_exp_f32_e32 v100, v126
	v_exp_f32_e32 v101, v127
	v_add_f32_e32 v100, 1.0, v100
	v_add_f32_e32 v101, 1.0, v101
	v_rcp_f32_e32 v100, v100
	v_rcp_f32_e32 v101, v101
	s_nop 0
	v_pk_mul_f32 v[100:101], v[126:127], v[100:101]
	s_nop 0
	v_pk_mul_f32 v[100:101], v[110:111], v[100:101]
	s_nop 0
	v_cvt_pk_bf16_f32 v100, v100, v101
	v_exp_f32_e32 v101, v128
	s_nop 0
	v_add_f32_e32 v101, 1.0, v101
	v_rcp_f32_e32 v102, v101
	v_exp_f32_e32 v101, v129
	s_nop 0
	v_add_f32_e32 v101, 1.0, v101
	v_rcp_f32_e32 v103, v101
	s_nop 0
	v_pk_mul_f32 v[102:103], v[128:129], v[102:103]
	s_nop 0
	v_pk_mul_f32 v[102:103], v[112:113], v[102:103]
	s_nop 0
	v_cvt_pk_bf16_f32 v101, v102, v103
	global_store_dwordx4 v[164:165], v[98:101], off offset:16
	s_nop 1
	v_or_b32_e32 v98, 32, v187
	v_mad_i64_i32 v[98:99], s[12:13], v98, s69, v[166:167]
	v_lshl_add_u64 v[98:99], v[98:99], 0, v[168:169]
	v_lshl_add_u64 v[98:99], v[98:99], 0, v[0:1]
	v_exp_f32_e32 v0, v82
	s_nop 0
	v_add_f32_e32 v0, 1.0, v0
	v_rcp_f32_e32 v100, v0
	v_exp_f32_e32 v0, v83
	s_nop 0
	v_add_f32_e32 v0, 1.0, v0
	v_rcp_f32_e32 v101, v0
	v_exp_f32_e32 v0, v84
	v_pk_mul_f32 v[82:83], v[82:83], v[100:101]
	s_nop 0
	v_pk_mul_f32 v[66:67], v[66:67], v[82:83]
	v_add_f32_e32 v0, 1.0, v0
	v_rcp_f32_e32 v82, v0
	v_exp_f32_e32 v0, v85
	v_cvt_pk_bf16_f32 v66, v66, v67
	v_add_f32_e32 v0, 1.0, v0
	v_rcp_f32_e32 v83, v0
	v_exp_f32_e32 v0, v86
	v_pk_mul_f32 v[82:83], v[84:85], v[82:83]
	s_nop 0
	v_pk_mul_f32 v[68:69], v[68:69], v[82:83]
	v_add_f32_e32 v0, 1.0, v0
	v_cvt_pk_bf16_f32 v67, v68, v69
	v_rcp_f32_e32 v68, v0
	v_exp_f32_e32 v0, v87
	s_nop 0
	v_add_f32_e32 v0, 1.0, v0
	v_rcp_f32_e32 v69, v0
	v_exp_f32_e32 v0, v88
	v_pk_mul_f32 v[68:69], v[86:87], v[68:69]
	s_nop 0
	v_pk_mul_f32 v[68:69], v[70:71], v[68:69]
	v_add_f32_e32 v0, 1.0, v0
	v_rcp_f32_e32 v70, v0
	v_exp_f32_e32 v0, v89
	v_cvt_pk_bf16_f32 v68, v68, v69
	v_add_f32_e32 v0, 1.0, v0
	v_rcp_f32_e32 v71, v0
	v_exp_f32_e32 v0, v90
	v_pk_mul_f32 v[70:71], v[88:89], v[70:71]
	s_nop 0
	v_pk_mul_f32 v[70:71], v[72:73], v[70:71]
	v_add_f32_e32 v0, 1.0, v0
	v_cvt_pk_bf16_f32 v69, v70, v71
	global_store_dwordx4 v[98:99], v[66:69], off
	s_nop 1
	v_rcp_f32_e32 v66, v0
	v_exp_f32_e32 v0, v91
	s_nop 0
	v_add_f32_e32 v0, 1.0, v0
	v_rcp_f32_e32 v67, v0
	v_exp_f32_e32 v0, v92
	v_pk_mul_f32 v[66:67], v[90:91], v[66:67]
	s_nop 0
	v_pk_mul_f32 v[66:67], v[74:75], v[66:67]
	v_add_f32_e32 v0, 1.0, v0
	v_rcp_f32_e32 v68, v0
	v_exp_f32_e32 v0, v93
	v_cvt_pk_bf16_f32 v66, v66, v67
	v_add_f32_e32 v0, 1.0, v0
	v_rcp_f32_e32 v69, v0
	v_exp_f32_e32 v0, v94
	v_pk_mul_f32 v[68:69], v[92:93], v[68:69]
	s_nop 0
	v_pk_mul_f32 v[68:69], v[76:77], v[68:69]
	v_add_f32_e32 v0, 1.0, v0
	v_cvt_pk_bf16_f32 v67, v68, v69
	v_rcp_f32_e32 v68, v0
	v_exp_f32_e32 v0, v95
	s_nop 0
	v_add_f32_e32 v0, 1.0, v0
	v_rcp_f32_e32 v69, v0
	v_exp_f32_e32 v0, v96
	v_pk_mul_f32 v[68:69], v[94:95], v[68:69]
	s_nop 0
	v_pk_mul_f32 v[68:69], v[78:79], v[68:69]
	v_add_f32_e32 v0, 1.0, v0
	v_rcp_f32_e32 v70, v0
	v_exp_f32_e32 v0, v97
	v_cvt_pk_bf16_f32 v68, v68, v69
	v_add_f32_e32 v0, 1.0, v0
	v_rcp_f32_e32 v71, v0
; DI unsigned pk2(float lo, float hi) { f32x2 v = {lo, hi}; bf16x2v b = __builtin_convertvector(v, bf16x2v); return __builtin_bit_cast(unsigned, b); }
; DI float siluf_(float x) { return x * __builtin_amdgcn_rcpf(1.f + __builtin_amdgcn_exp2f(-LOG2E * x)); }
;   DI void operator()(int tok0, int feat0, f32x16 (&acc)[2][2], int r, int hh) const {
;     const int u0 = (feat0 >> 6) * 32;
; #pragma unroll
;     for (int mt = 0; mt < 2; ++mt) {
;       bf16_t* dst = act + (size_t)(tok0 + mt * 32 + r) * DFF + u0 + 16 * hh;
; #pragma unroll
;       for (int gp = 0; gp < 2; ++gp) {
;         u32x4 o;
; #pragma unroll
;         for (int q = 0; q < 4; ++q) { const int i = 8 * gp + 2 * q; o[q] = pk2(siluf_(acc[0][mt][i]) * acc[1][mt][i], siluf_(acc[0][mt][i + 1]) * acc[1][mt][i + 1]); }
;         *(u32x4*)(dst + 8 * gp) = o;
;       }
;     }
;   }
	s_nop 0
	v_pk_mul_f32 v[70:71], v[96:97], v[70:71]
	s_nop 0
	v_pk_mul_f32 v[70:71], v[80:81], v[70:71]
	s_nop 0
	v_cvt_pk_bf16_f32 v69, v70, v71
	global_store_dwordx4 v[98:99], v[66:69], off offset:16
	v_exp_f32_e32 v0, v50
	s_nop 0
	v_add_f32_e32 v0, 1.0, v0
	v_rcp_f32_e32 v66, v0
	v_exp_f32_e32 v0, v51
	s_nop 0
	v_add_f32_e32 v0, 1.0, v0
	v_rcp_f32_e32 v67, v0
	v_exp_f32_e32 v0, v52
	v_pk_mul_f32 v[50:51], v[50:51], v[66:67]
	s_nop 0
	v_pk_mul_f32 v[34:35], v[34:35], v[50:51]
	v_add_f32_e32 v0, 1.0, v0
	v_rcp_f32_e32 v50, v0
	v_exp_f32_e32 v0, v53
	v_cvt_pk_bf16_f32 v34, v34, v35
	v_add_f32_e32 v0, 1.0, v0
	v_rcp_f32_e32 v51, v0
	v_exp_f32_e32 v0, v54
	v_pk_mul_f32 v[50:51], v[52:53], v[50:51]
	s_nop 0
	v_pk_mul_f32 v[36:37], v[36:37], v[50:51]
	v_add_f32_e32 v0, 1.0, v0
	v_cvt_pk_bf16_f32 v35, v36, v37
	v_rcp_f32_e32 v36, v0
	v_exp_f32_e32 v0, v55
	s_nop 0
	v_add_f32_e32 v0, 1.0, v0
	v_rcp_f32_e32 v37, v0
	v_exp_f32_e32 v0, v56
	v_pk_mul_f32 v[36:37], v[54:55], v[36:37]
	s_nop 0
	v_pk_mul_f32 v[36:37], v[38:39], v[36:37]
	v_add_f32_e32 v0, 1.0, v0
	v_rcp_f32_e32 v38, v0
	v_exp_f32_e32 v0, v57
	v_cvt_pk_bf16_f32 v36, v36, v37
	v_add_f32_e32 v0, 1.0, v0
	v_rcp_f32_e32 v39, v0
	v_exp_f32_e32 v0, v58
	v_pk_mul_f32 v[38:39], v[56:57], v[38:39]
	s_nop 0
	v_pk_mul_f32 v[38:39], v[40:41], v[38:39]
	v_add_f32_e32 v0, 1.0, v0
	v_cvt_pk_bf16_f32 v37, v38, v39
	global_store_dwordx4 v[164:165], v[34:37], off offset:64
	s_nop 1
	v_rcp_f32_e32 v34, v0
	v_exp_f32_e32 v0, v59
	s_nop 0
	v_add_f32_e32 v0, 1.0, v0
	v_rcp_f32_e32 v35, v0
	v_exp_f32_e32 v0, v60
	v_pk_mul_f32 v[34:35], v[58:59], v[34:35]
	s_nop 0
	v_pk_mul_f32 v[34:35], v[42:43], v[34:35]
	v_add_f32_e32 v0, 1.0, v0
	v_rcp_f32_e32 v36, v0
	v_exp_f32_e32 v0, v61
	v_cvt_pk_bf16_f32 v34, v34, v35
	v_add_f32_e32 v0, 1.0, v0
	v_rcp_f32_e32 v37, v0
	v_exp_f32_e32 v0, v62
	v_pk_mul_f32 v[36:37], v[60:61], v[36:37]
	s_nop 0
	v_pk_mul_f32 v[36:37], v[44:45], v[36:37]
	v_add_f32_e32 v0, 1.0, v0
	v_cvt_pk_bf16_f32 v35, v36, v37
	v_rcp_f32_e32 v36, v0
	v_exp_f32_e32 v0, v63
	s_nop 0
	v_add_f32_e32 v0, 1.0, v0
	v_rcp_f32_e32 v37, v0
	v_exp_f32_e32 v0, v64
	v_pk_mul_f32 v[36:37], v[62:63], v[36:37]
	s_nop 0
	v_pk_mul_f32 v[36:37], v[46:47], v[36:37]
	v_add_f32_e32 v0, 1.0, v0
	v_rcp_f32_e32 v38, v0
	v_exp_f32_e32 v0, v65
	v_cvt_pk_bf16_f32 v36, v36, v37
	v_add_f32_e32 v0, 1.0, v0
	v_rcp_f32_e32 v39, v0
	v_exp_f32_e32 v0, v18
	v_pk_mul_f32 v[38:39], v[64:65], v[38:39]
	s_nop 0
	v_pk_mul_f32 v[38:39], v[48:49], v[38:39]
	v_add_f32_e32 v0, 1.0, v0
	v_cvt_pk_bf16_f32 v37, v38, v39
	global_store_dwordx4 v[164:165], v[34:37], off offset:80
	s_nop 1
	v_rcp_f32_e32 v34, v0
	v_exp_f32_e32 v0, v19
	s_nop 0
	v_add_f32_e32 v0, 1.0, v0
	v_rcp_f32_e32 v35, v0
	v_exp_f32_e32 v0, v20
	v_pk_mul_f32 v[18:19], v[18:19], v[34:35]
	s_nop 0
	v_pk_mul_f32 v[2:3], v[2:3], v[18:19]
	v_add_f32_e32 v0, 1.0, v0
	v_rcp_f32_e32 v18, v0
	v_exp_f32_e32 v0, v21
	v_cvt_pk_bf16_f32 v2, v2, v3
	v_add_f32_e32 v0, 1.0, v0
	v_rcp_f32_e32 v19, v0
	v_exp_f32_e32 v0, v22
	v_pk_mul_f32 v[18:19], v[20:21], v[18:19]
	s_nop 0
	v_pk_mul_f32 v[4:5], v[4:5], v[18:19]
	v_add_f32_e32 v0, 1.0, v0
	v_cvt_pk_bf16_f32 v3, v4, v5
	v_rcp_f32_e32 v4, v0
	v_exp_f32_e32 v0, v23
	s_nop 0
	v_add_f32_e32 v0, 1.0, v0
	v_rcp_f32_e32 v5, v0
	v_exp_f32_e32 v0, v24
	v_pk_mul_f32 v[4:5], v[22:23], v[4:5]
	s_nop 0
	v_pk_mul_f32 v[4:5], v[6:7], v[4:5]
	v_add_f32_e32 v0, 1.0, v0
	v_rcp_f32_e32 v6, v0
	v_exp_f32_e32 v0, v25
	v_cvt_pk_bf16_f32 v4, v4, v5
	v_add_f32_e32 v0, 1.0, v0
	v_rcp_f32_e32 v7, v0
	v_exp_f32_e32 v0, v26
	v_pk_mul_f32 v[6:7], v[24:25], v[6:7]
	s_nop 0
	v_pk_mul_f32 v[6:7], v[8:9], v[6:7]
	v_add_f32_e32 v0, 1.0, v0
	v_cvt_pk_bf16_f32 v5, v6, v7
	global_store_dwordx4 v[98:99], v[2:5], off offset:64
	s_nop 1
	v_rcp_f32_e32 v2, v0
	v_exp_f32_e32 v0, v27
	s_nop 0
	v_add_f32_e32 v0, 1.0, v0
	v_rcp_f32_e32 v3, v0
	v_exp_f32_e32 v0, v28
	v_pk_mul_f32 v[2:3], v[26:27], v[2:3]
	s_nop 0
	v_pk_mul_f32 v[2:3], v[10:11], v[2:3]
	v_add_f32_e32 v0, 1.0, v0
	v_rcp_f32_e32 v4, v0
	v_exp_f32_e32 v0, v29
	v_cvt_pk_bf16_f32 v2, v2, v3
	v_add_f32_e32 v0, 1.0, v0
	v_rcp_f32_e32 v5, v0
	v_exp_f32_e32 v0, v30
	v_pk_mul_f32 v[4:5], v[28:29], v[4:5]
	s_nop 0
	v_pk_mul_f32 v[4:5], v[12:13], v[4:5]
	v_add_f32_e32 v0, 1.0, v0
	v_cvt_pk_bf16_f32 v3, v4, v5
	v_rcp_f32_e32 v4, v0
	v_exp_f32_e32 v0, v31
	s_nop 0
	v_add_f32_e32 v0, 1.0, v0
	v_rcp_f32_e32 v5, v0
	v_exp_f32_e32 v0, v32
	v_pk_mul_f32 v[4:5], v[30:31], v[4:5]
	s_nop 0
	v_pk_mul_f32 v[4:5], v[14:15], v[4:5]
	v_add_f32_e32 v0, 1.0, v0
	v_rcp_f32_e32 v6, v0
	v_exp_f32_e32 v0, v33
	v_cvt_pk_bf16_f32 v4, v4, v5
	v_add_f32_e32 v0, 1.0, v0
	v_rcp_f32_e32 v7, v0
	s_nop 0
	v_pk_mul_f32 v[6:7], v[32:33], v[6:7]
	s_nop 0
	v_pk_mul_f32 v[6:7], v[16:17], v[6:7]
	s_nop 0
	v_cvt_pk_bf16_f32 v5, v6, v7
	global_store_dwordx4 v[98:99], v[2:5], off offset:80
	s_and_b64 vcc, exec, s[4:5]
	s_mov_b32 s16, s9
	s_cbranch_vccz .LBB0_736
	s_add_i32 s25, s24, 1
	s_cmp_ge_i32 s25, s79
	s_cbranch_scc1 .LBB0_762
	s_cmp_lg_u32 s24, s78
	s_mov_b64 s[4:5], -1
	v_mov_b32_e32 v206, v198
	v_mov_b32_e32 v207, v199
	s_cbranch_scc0 .LBB0_750
	s_waitcnt vmcnt(0)
	s_barrier
	s_mov_b64 s[4:5], exec
	v_readlane_b32 s2, v254, 26
	v_readlane_b32 s3, v254, 27
	s_and_b64 s[2:3], s[4:5], s[2:3]
	s_mov_b64 exec, s[2:3]
	s_cbranch_execz .LBB0_749
	s_load_dword s2, s[80:81], 0x0
	s_mov_b64 s[8:9], exec
	buffer_wbl2 sc1
	s_waitcnt vmcnt(0) lgkmcnt(0)
	s_waitcnt vmcnt(0)
	v_mbcnt_lo_u32_b32 v0, s8, 0
	s_add_u32 s6, s10, 0x1ee14400
	v_mbcnt_hi_u32_b32 v0, s9, v0
	s_addc_u32 s7, s11, 0
	v_cmp_eq_u32_e32 vcc, 0, v0
	s_and_saveexec_b64 s[10:11], vcc
	s_cbranch_execz .LBB0_746
	s_bcnt1_i32_b64 s3, s[8:9]
	v_mov_b32_e32 v0, s3
	global_atomic_add v1, v0, s[6:7]
